# diff-attention final epilogue rewritten: 16 wide stash loads in flight, packed math, DPP+swizzle row reduction, no per-row drains
# speedup vs baseline: 1.0438x; 1.0438x over previous
.LBB0_166:
	s_and_saveexec_b64 s[0:1], s[6:7]
	v_readlane_b32 s53, v254, 49
	ds_write_b32 v123, v64
	s_or_b64 exec, exec, s[0:1]
	global_load_dwordx4 v[68:71], v[112:113], off
	global_load_dwordx4 v[72:75], v[112:113], off offset:16
	global_load_dwordx4 v[76:79], v[112:113], off offset:32
	global_load_dwordx4 v[80:83], v[112:113], off offset:48
	global_load_dwordx4 v[84:87], v[112:113], off offset:64
	global_load_dwordx4 v[88:91], v[112:113], off offset:80
	global_load_dwordx4 v[92:95], v[112:113], off offset:96
	global_load_dwordx4 v[96:99], v[112:113], off offset:112
	global_load_dwordx4 v[100:103], v[112:113], off offset:128
	global_load_dwordx4 v[104:107], v[112:113], off offset:144
	global_load_dwordx4 v[108:111], v[112:113], off offset:160
	global_load_dwordx4 v[130:133], v[112:113], off offset:176
	global_load_dwordx4 v[134:137], v[112:113], off offset:192
	global_load_dwordx4 v[138:141], v[112:113], off offset:208
	global_load_dwordx4 v[146:149], v[112:113], off offset:224
	global_load_dwordx4 v[150:153], v[112:113], off offset:240
	v_and_b32_e32 v66, 31, v121
	v_lshlrev_b32_e32 v67, 2, v66
	global_load_dword v154, v67, s[10:11]
	global_load_dword v156, v67, s[10:11] offset:128
	global_load_dword v158, v67, s[10:11] offset:256
	global_load_dword v178, v67, s[10:11] offset:384
	v_add_u32_e32 v65, v122, v184
	s_waitcnt lgkmcnt(0)
	ds_read_b128 v[160:163], v65
	ds_read_b128 v[164:167], v65 offset:32
	ds_read_b128 v[168:171], v65 offset:64
	ds_read_b128 v[172:175], v65 offset:96
	v_ashrrev_i32_e32 v176, 1, v121
	v_and_b32_e32 v176, 0xffffffe0, v176
	v_ashrrev_i32_e32 v177, 31, v176
	v_lshl_add_u64 v[176:177], s[22:23], 0, v[176:177]
	v_lshrrev_b32_e32 v180, 3, v121
	v_and_or_b32 v176, v180, 4, v176
	v_lshlrev_b64 v[176:177], 11, v[176:177]
	v_lshl_add_u64 v[176:177], s[8:9], 0, v[176:177]
	s_lshl_b32 s88, s65, 1
	v_lshl_add_u64 v[176:177], v[176:177], 0, s[88:89]
	v_lshlrev_b32_e32 v184, 1, v66
	v_lshl_add_u64 v[176:177], v[176:177], 0, v[184:185]
	s_waitcnt lgkmcnt(0)
	v_rcp_f32_e32 v160, v160
	v_rcp_f32_e32 v161, v161
	v_rcp_f32_e32 v162, v162
	v_rcp_f32_e32 v163, v163
	v_rcp_f32_e32 v164, v164
	v_rcp_f32_e32 v165, v165
	v_rcp_f32_e32 v166, v166
	v_rcp_f32_e32 v167, v167
	v_rcp_f32_e32 v168, v168
	v_rcp_f32_e32 v169, v169
	v_rcp_f32_e32 v170, v170
	v_rcp_f32_e32 v171, v171
	v_rcp_f32_e32 v172, v172
	v_rcp_f32_e32 v173, v173
	v_rcp_f32_e32 v174, v174
	v_rcp_f32_e32 v175, v175
	v_pk_mul_f32 v[48:49], v[48:49], v[160:161]
	v_pk_mul_f32 v[50:51], v[50:51], v[162:163]
	v_pk_mul_f32 v[52:53], v[52:53], v[164:165]
	v_pk_mul_f32 v[54:55], v[54:55], v[166:167]
	v_pk_mul_f32 v[56:57], v[56:57], v[168:169]
	v_pk_mul_f32 v[58:59], v[58:59], v[170:171]
	v_pk_mul_f32 v[60:61], v[60:61], v[172:173]
	v_pk_mul_f32 v[62:63], v[62:63], v[174:175]
	v_pk_mul_f32 v[32:33], v[32:33], v[160:161]
	v_pk_mul_f32 v[34:35], v[34:35], v[162:163]
	v_pk_mul_f32 v[36:37], v[36:37], v[164:165]
	v_pk_mul_f32 v[38:39], v[38:39], v[166:167]
	v_pk_mul_f32 v[40:41], v[40:41], v[168:169]
	v_pk_mul_f32 v[42:43], v[42:43], v[170:171]
	v_pk_mul_f32 v[44:45], v[44:45], v[172:173]
	v_pk_mul_f32 v[46:47], v[46:47], v[174:175]
	v_pk_mul_f32 v[16:17], v[16:17], v[160:161]
	v_pk_mul_f32 v[18:19], v[18:19], v[162:163]
	v_pk_mul_f32 v[20:21], v[20:21], v[164:165]
	v_pk_mul_f32 v[22:23], v[22:23], v[166:167]
	v_pk_mul_f32 v[24:25], v[24:25], v[168:169]
	v_pk_mul_f32 v[26:27], v[26:27], v[170:171]
	v_pk_mul_f32 v[28:29], v[28:29], v[172:173]
	v_pk_mul_f32 v[30:31], v[30:31], v[174:175]
	v_pk_mul_f32 v[0:1], v[0:1], v[160:161]
	v_pk_mul_f32 v[2:3], v[2:3], v[162:163]
	v_pk_mul_f32 v[4:5], v[4:5], v[164:165]
	v_pk_mul_f32 v[6:7], v[6:7], v[166:167]
	v_pk_mul_f32 v[8:9], v[8:9], v[168:169]
	v_pk_mul_f32 v[10:11], v[10:11], v[170:171]
	v_pk_mul_f32 v[12:13], v[12:13], v[172:173]
	v_pk_mul_f32 v[14:15], v[14:15], v[174:175]
	s_waitcnt vmcnt(0)
	v_mul_f32_e32 v154, v157, v154
	v_mul_f32_e32 v156, v157, v156
	v_mul_f32_e32 v158, v157, v158
	v_mul_f32_e32 v178, v157, v178
	v_pk_fma_f32 v[48:49], v[144:145], v[48:49], v[68:69] neg_lo:[1,0,0] neg_hi:[1,0,0]
	v_pk_fma_f32 v[50:51], v[144:145], v[50:51], v[70:71] neg_lo:[1,0,0] neg_hi:[1,0,0]
	v_pk_fma_f32 v[52:53], v[144:145], v[52:53], v[72:73] neg_lo:[1,0,0] neg_hi:[1,0,0]
	v_pk_fma_f32 v[54:55], v[144:145], v[54:55], v[74:75] neg_lo:[1,0,0] neg_hi:[1,0,0]
	v_pk_fma_f32 v[56:57], v[144:145], v[56:57], v[76:77] neg_lo:[1,0,0] neg_hi:[1,0,0]
	v_pk_fma_f32 v[58:59], v[144:145], v[58:59], v[78:79] neg_lo:[1,0,0] neg_hi:[1,0,0]
	v_pk_fma_f32 v[60:61], v[144:145], v[60:61], v[80:81] neg_lo:[1,0,0] neg_hi:[1,0,0]
	v_pk_fma_f32 v[62:63], v[144:145], v[62:63], v[82:83] neg_lo:[1,0,0] neg_hi:[1,0,0]
	v_pk_fma_f32 v[32:33], v[144:145], v[32:33], v[84:85] neg_lo:[1,0,0] neg_hi:[1,0,0]
	v_pk_fma_f32 v[34:35], v[144:145], v[34:35], v[86:87] neg_lo:[1,0,0] neg_hi:[1,0,0]
	v_pk_fma_f32 v[36:37], v[144:145], v[36:37], v[88:89] neg_lo:[1,0,0] neg_hi:[1,0,0]
	v_pk_fma_f32 v[38:39], v[144:145], v[38:39], v[90:91] neg_lo:[1,0,0] neg_hi:[1,0,0]
	v_pk_fma_f32 v[40:41], v[144:145], v[40:41], v[92:93] neg_lo:[1,0,0] neg_hi:[1,0,0]
	v_pk_fma_f32 v[42:43], v[144:145], v[42:43], v[94:95] neg_lo:[1,0,0] neg_hi:[1,0,0]
	v_pk_fma_f32 v[44:45], v[144:145], v[44:45], v[96:97] neg_lo:[1,0,0] neg_hi:[1,0,0]
	v_pk_fma_f32 v[46:47], v[144:145], v[46:47], v[98:99] neg_lo:[1,0,0] neg_hi:[1,0,0]
	v_pk_fma_f32 v[16:17], v[144:145], v[16:17], v[100:101] neg_lo:[1,0,0] neg_hi:[1,0,0]
	v_pk_fma_f32 v[18:19], v[144:145], v[18:19], v[102:103] neg_lo:[1,0,0] neg_hi:[1,0,0]
	v_pk_fma_f32 v[20:21], v[144:145], v[20:21], v[104:105] neg_lo:[1,0,0] neg_hi:[1,0,0]
	v_pk_fma_f32 v[22:23], v[144:145], v[22:23], v[106:107] neg_lo:[1,0,0] neg_hi:[1,0,0]
	v_pk_fma_f32 v[24:25], v[144:145], v[24:25], v[108:109] neg_lo:[1,0,0] neg_hi:[1,0,0]
	v_pk_fma_f32 v[26:27], v[144:145], v[26:27], v[110:111] neg_lo:[1,0,0] neg_hi:[1,0,0]
	v_pk_fma_f32 v[28:29], v[144:145], v[28:29], v[130:131] neg_lo:[1,0,0] neg_hi:[1,0,0]
	v_pk_fma_f32 v[30:31], v[144:145], v[30:31], v[132:133] neg_lo:[1,0,0] neg_hi:[1,0,0]
	v_pk_fma_f32 v[0:1], v[144:145], v[0:1], v[134:135] neg_lo:[1,0,0] neg_hi:[1,0,0]
	v_pk_fma_f32 v[2:3], v[144:145], v[2:3], v[136:137] neg_lo:[1,0,0] neg_hi:[1,0,0]
	v_pk_fma_f32 v[4:5], v[144:145], v[4:5], v[138:139] neg_lo:[1,0,0] neg_hi:[1,0,0]
	v_pk_fma_f32 v[6:7], v[144:145], v[6:7], v[140:141] neg_lo:[1,0,0] neg_hi:[1,0,0]
	v_pk_fma_f32 v[8:9], v[144:145], v[8:9], v[146:147] neg_lo:[1,0,0] neg_hi:[1,0,0]
	v_pk_fma_f32 v[10:11], v[144:145], v[10:11], v[148:149] neg_lo:[1,0,0] neg_hi:[1,0,0]
	v_pk_fma_f32 v[12:13], v[144:145], v[12:13], v[150:151] neg_lo:[1,0,0] neg_hi:[1,0,0]
	v_pk_fma_f32 v[14:15], v[144:145], v[14:15], v[152:153] neg_lo:[1,0,0] neg_hi:[1,0,0]
	v_pk_mul_f32 v[68:69], v[48:49], v[48:49]
	v_pk_mul_f32 v[70:71], v[50:51], v[50:51]
	v_pk_mul_f32 v[72:73], v[52:53], v[52:53]
	v_pk_mul_f32 v[74:75], v[54:55], v[54:55]
	v_pk_mul_f32 v[76:77], v[56:57], v[56:57]
	v_pk_mul_f32 v[78:79], v[58:59], v[58:59]
	v_pk_mul_f32 v[80:81], v[60:61], v[60:61]
	v_pk_mul_f32 v[82:83], v[62:63], v[62:63]
	v_pk_fma_f32 v[68:69], v[32:33], v[32:33], v[68:69]
	v_pk_fma_f32 v[70:71], v[34:35], v[34:35], v[70:71]
	v_pk_fma_f32 v[72:73], v[36:37], v[36:37], v[72:73]
	v_pk_fma_f32 v[74:75], v[38:39], v[38:39], v[74:75]
	v_pk_fma_f32 v[76:77], v[40:41], v[40:41], v[76:77]
	v_pk_fma_f32 v[78:79], v[42:43], v[42:43], v[78:79]
	v_pk_fma_f32 v[80:81], v[44:45], v[44:45], v[80:81]
	v_pk_fma_f32 v[82:83], v[46:47], v[46:47], v[82:83]
	v_pk_fma_f32 v[68:69], v[16:17], v[16:17], v[68:69]
	v_pk_fma_f32 v[70:71], v[18:19], v[18:19], v[70:71]
	v_pk_fma_f32 v[72:73], v[20:21], v[20:21], v[72:73]
	v_pk_fma_f32 v[74:75], v[22:23], v[22:23], v[74:75]
	v_pk_fma_f32 v[76:77], v[24:25], v[24:25], v[76:77]
	v_pk_fma_f32 v[78:79], v[26:27], v[26:27], v[78:79]
	v_pk_fma_f32 v[80:81], v[28:29], v[28:29], v[80:81]
	v_pk_fma_f32 v[82:83], v[30:31], v[30:31], v[82:83]
	v_pk_fma_f32 v[68:69], v[0:1], v[0:1], v[68:69]
	v_pk_fma_f32 v[70:71], v[2:3], v[2:3], v[70:71]
	v_pk_fma_f32 v[72:73], v[4:5], v[4:5], v[72:73]
	v_pk_fma_f32 v[74:75], v[6:7], v[6:7], v[74:75]
	v_pk_fma_f32 v[76:77], v[8:9], v[8:9], v[76:77]
	v_pk_fma_f32 v[78:79], v[10:11], v[10:11], v[78:79]
	v_pk_fma_f32 v[80:81], v[12:13], v[12:13], v[80:81]
	v_pk_fma_f32 v[82:83], v[14:15], v[14:15], v[82:83]
	v_add_f32_dpp v68, v68, v68 quad_perm:[1,0,3,2] row_mask:0xf bank_mask:0xf
	v_add_f32_dpp v69, v69, v69 quad_perm:[1,0,3,2] row_mask:0xf bank_mask:0xf
	v_add_f32_dpp v70, v70, v70 quad_perm:[1,0,3,2] row_mask:0xf bank_mask:0xf
	v_add_f32_dpp v71, v71, v71 quad_perm:[1,0,3,2] row_mask:0xf bank_mask:0xf
	v_add_f32_dpp v72, v72, v72 quad_perm:[1,0,3,2] row_mask:0xf bank_mask:0xf
	v_add_f32_dpp v73, v73, v73 quad_perm:[1,0,3,2] row_mask:0xf bank_mask:0xf
	v_add_f32_dpp v74, v74, v74 quad_perm:[1,0,3,2] row_mask:0xf bank_mask:0xf
	v_add_f32_dpp v75, v75, v75 quad_perm:[1,0,3,2] row_mask:0xf bank_mask:0xf
	v_add_f32_dpp v76, v76, v76 quad_perm:[1,0,3,2] row_mask:0xf bank_mask:0xf
	v_add_f32_dpp v77, v77, v77 quad_perm:[1,0,3,2] row_mask:0xf bank_mask:0xf
	v_add_f32_dpp v78, v78, v78 quad_perm:[1,0,3,2] row_mask:0xf bank_mask:0xf
	v_add_f32_dpp v79, v79, v79 quad_perm:[1,0,3,2] row_mask:0xf bank_mask:0xf
	v_add_f32_dpp v80, v80, v80 quad_perm:[1,0,3,2] row_mask:0xf bank_mask:0xf
	v_add_f32_dpp v81, v81, v81 quad_perm:[1,0,3,2] row_mask:0xf bank_mask:0xf
	v_add_f32_dpp v82, v82, v82 quad_perm:[1,0,3,2] row_mask:0xf bank_mask:0xf
	v_add_f32_dpp v83, v83, v83 quad_perm:[1,0,3,2] row_mask:0xf bank_mask:0xf
	v_add_f32_dpp v68, v68, v68 quad_perm:[2,3,0,1] row_mask:0xf bank_mask:0xf
	v_add_f32_dpp v69, v69, v69 quad_perm:[2,3,0,1] row_mask:0xf bank_mask:0xf
	v_add_f32_dpp v70, v70, v70 quad_perm:[2,3,0,1] row_mask:0xf bank_mask:0xf
	v_add_f32_dpp v71, v71, v71 quad_perm:[2,3,0,1] row_mask:0xf bank_mask:0xf
	v_add_f32_dpp v72, v72, v72 quad_perm:[2,3,0,1] row_mask:0xf bank_mask:0xf
	v_add_f32_dpp v73, v73, v73 quad_perm:[2,3,0,1] row_mask:0xf bank_mask:0xf
	v_add_f32_dpp v74, v74, v74 quad_perm:[2,3,0,1] row_mask:0xf bank_mask:0xf
	v_add_f32_dpp v75, v75, v75 quad_perm:[2,3,0,1] row_mask:0xf bank_mask:0xf
	v_add_f32_dpp v76, v76, v76 quad_perm:[2,3,0,1] row_mask:0xf bank_mask:0xf
	v_add_f32_dpp v77, v77, v77 quad_perm:[2,3,0,1] row_mask:0xf bank_mask:0xf
	v_add_f32_dpp v78, v78, v78 quad_perm:[2,3,0,1] row_mask:0xf bank_mask:0xf
	v_add_f32_dpp v79, v79, v79 quad_perm:[2,3,0,1] row_mask:0xf bank_mask:0xf
	v_add_f32_dpp v80, v80, v80 quad_perm:[2,3,0,1] row_mask:0xf bank_mask:0xf
	v_add_f32_dpp v81, v81, v81 quad_perm:[2,3,0,1] row_mask:0xf bank_mask:0xf
	v_add_f32_dpp v82, v82, v82 quad_perm:[2,3,0,1] row_mask:0xf bank_mask:0xf
	v_add_f32_dpp v83, v83, v83 quad_perm:[2,3,0,1] row_mask:0xf bank_mask:0xf
	v_add_f32_dpp v68, v68, v68 row_half_mirror row_mask:0xf bank_mask:0xf
	v_add_f32_dpp v69, v69, v69 row_half_mirror row_mask:0xf bank_mask:0xf
	v_add_f32_dpp v70, v70, v70 row_half_mirror row_mask:0xf bank_mask:0xf
	v_add_f32_dpp v71, v71, v71 row_half_mirror row_mask:0xf bank_mask:0xf
	v_add_f32_dpp v72, v72, v72 row_half_mirror row_mask:0xf bank_mask:0xf
	v_add_f32_dpp v73, v73, v73 row_half_mirror row_mask:0xf bank_mask:0xf
	v_add_f32_dpp v74, v74, v74 row_half_mirror row_mask:0xf bank_mask:0xf
	v_add_f32_dpp v75, v75, v75 row_half_mirror row_mask:0xf bank_mask:0xf
	v_add_f32_dpp v76, v76, v76 row_half_mirror row_mask:0xf bank_mask:0xf
	v_add_f32_dpp v77, v77, v77 row_half_mirror row_mask:0xf bank_mask:0xf
	v_add_f32_dpp v78, v78, v78 row_half_mirror row_mask:0xf bank_mask:0xf
	v_add_f32_dpp v79, v79, v79 row_half_mirror row_mask:0xf bank_mask:0xf
	v_add_f32_dpp v80, v80, v80 row_half_mirror row_mask:0xf bank_mask:0xf
	v_add_f32_dpp v81, v81, v81 row_half_mirror row_mask:0xf bank_mask:0xf
	v_add_f32_dpp v82, v82, v82 row_half_mirror row_mask:0xf bank_mask:0xf
	v_add_f32_dpp v83, v83, v83 row_half_mirror row_mask:0xf bank_mask:0xf
	v_add_f32_dpp v68, v68, v68 row_mirror row_mask:0xf bank_mask:0xf
	v_add_f32_dpp v69, v69, v69 row_mirror row_mask:0xf bank_mask:0xf
	v_add_f32_dpp v70, v70, v70 row_mirror row_mask:0xf bank_mask:0xf
	v_add_f32_dpp v71, v71, v71 row_mirror row_mask:0xf bank_mask:0xf
	v_add_f32_dpp v72, v72, v72 row_mirror row_mask:0xf bank_mask:0xf
	v_add_f32_dpp v73, v73, v73 row_mirror row_mask:0xf bank_mask:0xf
	v_add_f32_dpp v74, v74, v74 row_mirror row_mask:0xf bank_mask:0xf
	v_add_f32_dpp v75, v75, v75 row_mirror row_mask:0xf bank_mask:0xf
	v_add_f32_dpp v76, v76, v76 row_mirror row_mask:0xf bank_mask:0xf
	v_add_f32_dpp v77, v77, v77 row_mirror row_mask:0xf bank_mask:0xf
	v_add_f32_dpp v78, v78, v78 row_mirror row_mask:0xf bank_mask:0xf
	v_add_f32_dpp v79, v79, v79 row_mirror row_mask:0xf bank_mask:0xf
	v_add_f32_dpp v80, v80, v80 row_mirror row_mask:0xf bank_mask:0xf
	v_add_f32_dpp v81, v81, v81 row_mirror row_mask:0xf bank_mask:0xf
	v_add_f32_dpp v82, v82, v82 row_mirror row_mask:0xf bank_mask:0xf
	v_add_f32_dpp v83, v83, v83 row_mirror row_mask:0xf bank_mask:0xf
	ds_swizzle_b32 v84, v68 offset:0x401f
	ds_swizzle_b32 v85, v69 offset:0x401f
	ds_swizzle_b32 v86, v70 offset:0x401f
	ds_swizzle_b32 v87, v71 offset:0x401f
	ds_swizzle_b32 v88, v72 offset:0x401f
	ds_swizzle_b32 v89, v73 offset:0x401f
	ds_swizzle_b32 v90, v74 offset:0x401f
	ds_swizzle_b32 v91, v75 offset:0x401f
	ds_swizzle_b32 v92, v76 offset:0x401f
	ds_swizzle_b32 v93, v77 offset:0x401f
	ds_swizzle_b32 v94, v78 offset:0x401f
	ds_swizzle_b32 v95, v79 offset:0x401f
	ds_swizzle_b32 v96, v80 offset:0x401f
	ds_swizzle_b32 v97, v81 offset:0x401f
	ds_swizzle_b32 v98, v82 offset:0x401f
	ds_swizzle_b32 v99, v83 offset:0x401f
	s_waitcnt lgkmcnt(0)
	v_pk_add_f32 v[68:69], v[68:69], v[84:85]
	v_pk_add_f32 v[70:71], v[70:71], v[86:87]
	v_pk_add_f32 v[72:73], v[72:73], v[88:89]
	v_pk_add_f32 v[74:75], v[74:75], v[90:91]
	v_pk_add_f32 v[76:77], v[76:77], v[92:93]
	v_pk_add_f32 v[78:79], v[78:79], v[94:95]
	v_pk_add_f32 v[80:81], v[80:81], v[96:97]
	v_pk_add_f32 v[82:83], v[82:83], v[98:99]
	v_fmamk_f32 v68, v68, 0x3c000000, v219
	v_fmamk_f32 v69, v69, 0x3c000000, v219
	v_fmamk_f32 v70, v70, 0x3c000000, v219
	v_fmamk_f32 v71, v71, 0x3c000000, v219
	v_fmamk_f32 v72, v72, 0x3c000000, v219
	v_fmamk_f32 v73, v73, 0x3c000000, v219
	v_fmamk_f32 v74, v74, 0x3c000000, v219
	v_fmamk_f32 v75, v75, 0x3c000000, v219
	v_fmamk_f32 v76, v76, 0x3c000000, v219
	v_fmamk_f32 v77, v77, 0x3c000000, v219
	v_fmamk_f32 v78, v78, 0x3c000000, v219
	v_fmamk_f32 v79, v79, 0x3c000000, v219
	v_fmamk_f32 v80, v80, 0x3c000000, v219
	v_fmamk_f32 v81, v81, 0x3c000000, v219
	v_fmamk_f32 v82, v82, 0x3c000000, v219
	v_fmamk_f32 v83, v83, 0x3c000000, v219
	v_rsq_f32_e32 v68, v68
	v_rsq_f32_e32 v69, v69
	v_rsq_f32_e32 v70, v70
	v_rsq_f32_e32 v71, v71
	v_rsq_f32_e32 v72, v72
	v_rsq_f32_e32 v73, v73
	v_rsq_f32_e32 v74, v74
	v_rsq_f32_e32 v75, v75
	v_rsq_f32_e32 v76, v76
	v_rsq_f32_e32 v77, v77
	v_rsq_f32_e32 v78, v78
	v_rsq_f32_e32 v79, v79
	v_rsq_f32_e32 v80, v80
	v_rsq_f32_e32 v81, v81
	v_rsq_f32_e32 v82, v82
	v_rsq_f32_e32 v83, v83
	v_pk_mul_f32 v[48:49], v[48:49], v[68:69]
	v_pk_mul_f32 v[50:51], v[50:51], v[70:71]
	v_pk_mul_f32 v[52:53], v[52:53], v[72:73]
	v_pk_mul_f32 v[54:55], v[54:55], v[74:75]
	v_pk_mul_f32 v[56:57], v[56:57], v[76:77]
	v_pk_mul_f32 v[58:59], v[58:59], v[78:79]
	v_pk_mul_f32 v[60:61], v[60:61], v[80:81]
	v_pk_mul_f32 v[62:63], v[62:63], v[82:83]
	v_pk_mul_f32 v[32:33], v[32:33], v[68:69]
	v_pk_mul_f32 v[34:35], v[34:35], v[70:71]
	v_pk_mul_f32 v[36:37], v[36:37], v[72:73]
	v_pk_mul_f32 v[38:39], v[38:39], v[74:75]
	v_pk_mul_f32 v[40:41], v[40:41], v[76:77]
	v_pk_mul_f32 v[42:43], v[42:43], v[78:79]
	v_pk_mul_f32 v[44:45], v[44:45], v[80:81]
	v_pk_mul_f32 v[46:47], v[46:47], v[82:83]
	v_pk_mul_f32 v[16:17], v[16:17], v[68:69]
	v_pk_mul_f32 v[18:19], v[18:19], v[70:71]
	v_pk_mul_f32 v[20:21], v[20:21], v[72:73]
	v_pk_mul_f32 v[22:23], v[22:23], v[74:75]
	v_pk_mul_f32 v[24:25], v[24:25], v[76:77]
	v_pk_mul_f32 v[26:27], v[26:27], v[78:79]
	v_pk_mul_f32 v[28:29], v[28:29], v[80:81]
	v_pk_mul_f32 v[30:31], v[30:31], v[82:83]
	v_pk_mul_f32 v[0:1], v[0:1], v[68:69]
	v_pk_mul_f32 v[2:3], v[2:3], v[70:71]
	v_pk_mul_f32 v[4:5], v[4:5], v[72:73]
	v_pk_mul_f32 v[6:7], v[6:7], v[74:75]
	v_pk_mul_f32 v[8:9], v[8:9], v[76:77]
	v_pk_mul_f32 v[10:11], v[10:11], v[78:79]
	v_pk_mul_f32 v[12:13], v[12:13], v[80:81]
	v_pk_mul_f32 v[14:15], v[14:15], v[82:83]
	v_pk_mul_f32 v[48:49], v[48:49], v[154:155] op_sel_hi:[1,0]
	v_pk_mul_f32 v[50:51], v[50:51], v[154:155] op_sel_hi:[1,0]
	v_pk_mul_f32 v[52:53], v[52:53], v[154:155] op_sel_hi:[1,0]
	v_pk_mul_f32 v[54:55], v[54:55], v[154:155] op_sel_hi:[1,0]
	v_pk_mul_f32 v[56:57], v[56:57], v[154:155] op_sel_hi:[1,0]
	v_pk_mul_f32 v[58:59], v[58:59], v[154:155] op_sel_hi:[1,0]
	v_pk_mul_f32 v[60:61], v[60:61], v[154:155] op_sel_hi:[1,0]
	v_pk_mul_f32 v[62:63], v[62:63], v[154:155] op_sel_hi:[1,0]
	v_pk_mul_f32 v[32:33], v[32:33], v[156:157] op_sel_hi:[1,0]
	v_pk_mul_f32 v[34:35], v[34:35], v[156:157] op_sel_hi:[1,0]
	v_pk_mul_f32 v[36:37], v[36:37], v[156:157] op_sel_hi:[1,0]
	v_pk_mul_f32 v[38:39], v[38:39], v[156:157] op_sel_hi:[1,0]
	v_pk_mul_f32 v[40:41], v[40:41], v[156:157] op_sel_hi:[1,0]
	v_pk_mul_f32 v[42:43], v[42:43], v[156:157] op_sel_hi:[1,0]
	v_pk_mul_f32 v[44:45], v[44:45], v[156:157] op_sel_hi:[1,0]
	v_pk_mul_f32 v[46:47], v[46:47], v[156:157] op_sel_hi:[1,0]
	v_pk_mul_f32 v[16:17], v[16:17], v[158:159] op_sel_hi:[1,0]
	v_pk_mul_f32 v[18:19], v[18:19], v[158:159] op_sel_hi:[1,0]
	v_pk_mul_f32 v[20:21], v[20:21], v[158:159] op_sel_hi:[1,0]
	v_pk_mul_f32 v[22:23], v[22:23], v[158:159] op_sel_hi:[1,0]
	v_pk_mul_f32 v[24:25], v[24:25], v[158:159] op_sel_hi:[1,0]
	v_pk_mul_f32 v[26:27], v[26:27], v[158:159] op_sel_hi:[1,0]
	v_pk_mul_f32 v[28:29], v[28:29], v[158:159] op_sel_hi:[1,0]
	v_pk_mul_f32 v[30:31], v[30:31], v[158:159] op_sel_hi:[1,0]
	v_pk_mul_f32 v[0:1], v[0:1], v[178:179] op_sel_hi:[1,0]
	v_pk_mul_f32 v[2:3], v[2:3], v[178:179] op_sel_hi:[1,0]
	v_pk_mul_f32 v[4:5], v[4:5], v[178:179] op_sel_hi:[1,0]
	v_pk_mul_f32 v[6:7], v[6:7], v[178:179] op_sel_hi:[1,0]
	v_pk_mul_f32 v[8:9], v[8:9], v[178:179] op_sel_hi:[1,0]
	v_pk_mul_f32 v[10:11], v[10:11], v[178:179] op_sel_hi:[1,0]
	v_pk_mul_f32 v[12:13], v[12:13], v[178:179] op_sel_hi:[1,0]
	v_pk_mul_f32 v[14:15], v[14:15], v[178:179] op_sel_hi:[1,0]
	v_cvt_pk_bf16_f32 v48, v48, v48
	v_cvt_pk_bf16_f32 v49, v49, v49
	v_cvt_pk_bf16_f32 v50, v50, v50
	v_cvt_pk_bf16_f32 v51, v51, v51
	v_cvt_pk_bf16_f32 v52, v52, v52
	v_cvt_pk_bf16_f32 v53, v53, v53
	v_cvt_pk_bf16_f32 v54, v54, v54
	v_cvt_pk_bf16_f32 v55, v55, v55
	v_cvt_pk_bf16_f32 v56, v56, v56
	v_cvt_pk_bf16_f32 v57, v57, v57
	v_cvt_pk_bf16_f32 v58, v58, v58
	v_cvt_pk_bf16_f32 v59, v59, v59
	v_cvt_pk_bf16_f32 v60, v60, v60
	v_cvt_pk_bf16_f32 v61, v61, v61
	v_cvt_pk_bf16_f32 v62, v62, v62
	v_cvt_pk_bf16_f32 v63, v63, v63
	v_cvt_pk_bf16_f32 v32, v32, v32
	v_cvt_pk_bf16_f32 v33, v33, v33
	v_cvt_pk_bf16_f32 v34, v34, v34
	v_cvt_pk_bf16_f32 v35, v35, v35
	v_cvt_pk_bf16_f32 v36, v36, v36
	v_cvt_pk_bf16_f32 v37, v37, v37
	v_cvt_pk_bf16_f32 v38, v38, v38
	v_cvt_pk_bf16_f32 v39, v39, v39
	v_cvt_pk_bf16_f32 v40, v40, v40
	v_cvt_pk_bf16_f32 v41, v41, v41
	v_cvt_pk_bf16_f32 v42, v42, v42
	v_cvt_pk_bf16_f32 v43, v43, v43
	v_cvt_pk_bf16_f32 v44, v44, v44
	v_cvt_pk_bf16_f32 v45, v45, v45
	v_cvt_pk_bf16_f32 v46, v46, v46
	v_cvt_pk_bf16_f32 v47, v47, v47
	v_cvt_pk_bf16_f32 v16, v16, v16
	v_cvt_pk_bf16_f32 v17, v17, v17
	v_cvt_pk_bf16_f32 v18, v18, v18
	v_cvt_pk_bf16_f32 v19, v19, v19
	v_cvt_pk_bf16_f32 v20, v20, v20
	v_cvt_pk_bf16_f32 v21, v21, v21
	v_cvt_pk_bf16_f32 v22, v22, v22
	v_cvt_pk_bf16_f32 v23, v23, v23
	v_cvt_pk_bf16_f32 v24, v24, v24
	v_cvt_pk_bf16_f32 v25, v25, v25
	v_cvt_pk_bf16_f32 v26, v26, v26
	v_cvt_pk_bf16_f32 v27, v27, v27
	v_cvt_pk_bf16_f32 v28, v28, v28
	v_cvt_pk_bf16_f32 v29, v29, v29
	v_cvt_pk_bf16_f32 v30, v30, v30
	v_cvt_pk_bf16_f32 v31, v31, v31
	v_cvt_pk_bf16_f32 v0, v0, v0
	v_cvt_pk_bf16_f32 v1, v1, v1
	v_cvt_pk_bf16_f32 v2, v2, v2
	v_cvt_pk_bf16_f32 v3, v3, v3
	v_cvt_pk_bf16_f32 v4, v4, v4
	v_cvt_pk_bf16_f32 v5, v5, v5
	v_cvt_pk_bf16_f32 v6, v6, v6
	v_cvt_pk_bf16_f32 v7, v7, v7
	v_cvt_pk_bf16_f32 v8, v8, v8
	v_cvt_pk_bf16_f32 v9, v9, v9
	v_cvt_pk_bf16_f32 v10, v10, v10
	v_cvt_pk_bf16_f32 v11, v11, v11
	v_cvt_pk_bf16_f32 v12, v12, v12
	v_cvt_pk_bf16_f32 v13, v13, v13
	v_cvt_pk_bf16_f32 v14, v14, v14
	v_cvt_pk_bf16_f32 v15, v15, v15
	global_store_short v[176:177], v48, off
	global_store_short v[176:177], v32, off offset:64
	global_store_short v[176:177], v16, off offset:128
	global_store_short v[176:177], v0, off offset:192
	global_store_short v[176:177], v49, off offset:2048
	global_store_short v[176:177], v33, off offset:2112
	global_store_short v[176:177], v17, off offset:2176
	global_store_short v[176:177], v1, off offset:2240
	s_mov_b64 s[0:1], 0x1000
	v_lshl_add_u64 v[182:183], v[176:177], 0, s[0:1]
	global_store_short v[182:183], v50, off
	global_store_short v[182:183], v34, off offset:64
	global_store_short v[182:183], v18, off offset:128
	global_store_short v[182:183], v2, off offset:192
	global_store_short v[182:183], v51, off offset:2048
	global_store_short v[182:183], v35, off offset:2112
	global_store_short v[182:183], v19, off offset:2176
	global_store_short v[182:183], v3, off offset:2240
	s_mov_b64 s[0:1], 0x4000
	v_lshl_add_u64 v[180:181], v[176:177], 0, s[0:1]
	global_store_short v[180:181], v52, off
	global_store_short v[180:181], v36, off offset:64
	global_store_short v[180:181], v20, off offset:128
	global_store_short v[180:181], v4, off offset:192
	global_store_short v[180:181], v53, off offset:2048
	global_store_short v[180:181], v37, off offset:2112
	global_store_short v[180:181], v21, off offset:2176
	global_store_short v[180:181], v5, off offset:2240
	s_mov_b64 s[0:1], 0x5000
	v_lshl_add_u64 v[182:183], v[176:177], 0, s[0:1]
	global_store_short v[182:183], v54, off
	global_store_short v[182:183], v38, off offset:64
	global_store_short v[182:183], v22, off offset:128
	global_store_short v[182:183], v6, off offset:192
	global_store_short v[182:183], v55, off offset:2048
	global_store_short v[182:183], v39, off offset:2112
	global_store_short v[182:183], v23, off offset:2176
	global_store_short v[182:183], v7, off offset:2240
	s_mov_b64 s[0:1], 0x8000
	v_lshl_add_u64 v[180:181], v[176:177], 0, s[0:1]
	global_store_short v[180:181], v56, off
	global_store_short v[180:181], v40, off offset:64
	global_store_short v[180:181], v24, off offset:128
	global_store_short v[180:181], v8, off offset:192
	global_store_short v[180:181], v57, off offset:2048
	global_store_short v[180:181], v41, off offset:2112
	global_store_short v[180:181], v25, off offset:2176
	global_store_short v[180:181], v9, off offset:2240
	s_mov_b64 s[0:1], 0x9000
	v_lshl_add_u64 v[182:183], v[176:177], 0, s[0:1]
	global_store_short v[182:183], v58, off
	global_store_short v[182:183], v42, off offset:64
	global_store_short v[182:183], v26, off offset:128
	global_store_short v[182:183], v10, off offset:192
	global_store_short v[182:183], v59, off offset:2048
	global_store_short v[182:183], v43, off offset:2112
	global_store_short v[182:183], v27, off offset:2176
	global_store_short v[182:183], v11, off offset:2240
	s_mov_b64 s[0:1], 0xc000
	v_lshl_add_u64 v[180:181], v[176:177], 0, s[0:1]
	global_store_short v[180:181], v60, off
	global_store_short v[180:181], v44, off offset:64
	global_store_short v[180:181], v28, off offset:128
	global_store_short v[180:181], v12, off offset:192
	global_store_short v[180:181], v61, off offset:2048
	global_store_short v[180:181], v45, off offset:2112
	global_store_short v[180:181], v29, off offset:2176
	global_store_short v[180:181], v13, off offset:2240
	s_mov_b64 s[0:1], 0xd000
	v_lshl_add_u64 v[182:183], v[176:177], 0, s[0:1]
	global_store_short v[182:183], v62, off
	global_store_short v[182:183], v46, off offset:64
	global_store_short v[182:183], v30, off offset:128
	global_store_short v[182:183], v14, off offset:192
	global_store_short v[182:183], v63, off offset:2048
	global_store_short v[182:183], v47, off offset:2112
	global_store_short v[182:183], v31, off offset:2176
	s_mov_b64 s[0:1], 0xd800
	v_mov_b32_e32 v2, v15
	v_lshl_add_u64 v[0:1], v[176:177], 0, s[0:1]
	s_branch .LBB0_129
